# v14 = v12 + next-block prefetch: next causal unit's K0/V0/K1 DMA, bound loads, rope table and Q rows issued at the top of the previous unit's epilogue
# speedup vs baseline: 1.0032x; 1.0014x over previous
.LBB0_546:
	s_or_b64 exec, exec, s[0:1]
	s_lshl_b64 s[0:1], s[56:57], 24
	v_readlane_b32 s8, v246, 45
	v_readlane_b32 s9, v246, 46
	s_add_u32 s8, s8, s0
	s_addc_u32 s9, s9, s1
	s_add_u32 s44, s8, s58
	s_addc_u32 s45, s9, s59
	v_readlane_b32 s8, v246, 47
	v_readlane_b32 s9, v246, 48
	s_add_u32 s0, s8, s0
	s_addc_u32 s1, s9, s1
	s_add_u32 s8, s0, s58
	s_addc_u32 s9, s1, s59
	s_lshl_b64 s[0:1], s[52:53], 11
	s_add_u32 s44, s44, s0
	s_addc_u32 s45, s45, s1
	s_add_u32 s0, s8, s0
	s_addc_u32 s1, s9, s1
	v_mov_b32_e32 v145, v153
	s_add_i32 s78, s78, 1
	v_lshl_add_u64 v[80:81], s[44:45], 0, v[144:145]
	v_lshl_add_u64 v[82:83], s[0:1], 0, v[144:145]
	s_cmp_eq_u32 s78, 3
	s_cbranch_scc1 .Lnbp_skip
	s_cmp_lt_i32 s78, 1
	s_mov_b32 s62, s70
	s_cbranch_scc1 .Lnbp_552
	s_cmp_lg_u32 s78, 1
	s_mov_b64 s[0:1], -1
	s_cbranch_scc0 .Lnbp_550
	s_mov_b64 s[0:1], 0

.Lnbp_556:
	s_or_b64 exec, exec, s[60:61]
	s_lshl_b64 s[60:61], s[56:57], 18
	v_readlane_b32 s1, v246, 39
	s_add_u32 s1, s1, s44
	v_readlane_b32 s44, v246, 40
	s_addc_u32 s44, s44, s45
	s_add_u32 s1, s1, s48
	s_addc_u32 s48, s44, s49
	s_lshl_b64 s[44:45], s[60:61], 2
	v_readlane_b32 s49, v246, 51
	s_add_u32 s44, s49, s44
	v_readlane_b32 s49, v246, 52
	s_addc_u32 s45, s49, s45
	s_lshl_b32 s81, s62, 8
	s_add_i32 s52, s81, s71
	v_or_b32_e32 v76, s52, v170
	v_mov_b32_e32 v77, v153
	v_lshlrev_b64 v[76:77], 7, v[76:77]
	v_lshl_add_u64 v[76:77], s[44:45], 0, v[76:77]
	v_lshl_add_u64 v[72:73], v[146:147], 2, v[76:77]
	s_mul_i32 s44, s52, 0x900
	s_mov_b32 s98, s0
	s_ashr_i32 s99, s0, 31
	s_lshl_b64 s[98:99], s[98:99], 9
	s_lshl_b32 s100, s56, 7
	s_ashr_i32 s101, s100, 31
	v_lshl_add_u64 v[250:251], v[162:163], 0, s[98:99]
	v_lshl_add_u64 v[252:253], s[100:101], 2, v[164:165]
	global_load_dword v247, v[250:251], off
	global_load_dword v248, v[250:251], off offset:256
	global_load_dword v249, v[252:253], off
	global_load_dword v254, v[252:253], off offset:256
	global_load_dwordx4 v[48:51], v[72:73], off
	global_load_dwordx4 v[52:55], v[72:73], off offset:16
	s_mul_hi_u32 s45, s52, 0x900
	global_load_dwordx4 v[56:59], v[72:73], off offset:48
	s_nop 0
	global_load_dwordx4 v[60:63], v[72:73], off offset:32
	s_add_u32 s44, s1, s44
	s_addc_u32 s45, s48, s45
	v_lshl_add_u64 v[78:79], s[44:45], 0, v[152:153]
	v_lshl_add_u64 v[74:75], v[150:151], 1, v[78:79]
	global_load_dwordx4 v[64:67], v[74:75], off offset:128
	global_load_dwordx4 v[68:71], v[74:75], off offset:160
	global_load_dwordx4 v[116:119], v[74:75], off
	global_load_dwordx4 v[112:115], v[74:75], off offset:32
	global_load_dwordx4 v[104:107], v[74:75], off offset:64
	global_load_dwordx4 v[96:99], v[74:75], off offset:96
.Lnbp_skip:
	s_waitcnt lgkmcnt(0)
	ds_read_b128 v[32:35], v215 offset:128
	ds_read_b128 v[36:39], v215 offset:160
	s_waitcnt lgkmcnt(1)
	v_rcp_f32_e32 v40, v32
	v_rcp_f32_e32 v41, v33
	v_mul_f32_e32 v0, v0, v40
	v_cvt_pk_bf16_f32 v0, v0, s0
	v_rcp_f32_e32 v42, v34
	ds_write_b16 v217, v0 offset:64
	v_mul_f32_e32 v0, v17, v41
	v_cvt_pk_bf16_f32 v0, v0, s0
	ds_write_b16 v217, v0 offset:128
	v_mul_f32_e32 v0, v1, v41
	v_cvt_pk_bf16_f32 v0, v0, s0
	v_rcp_f32_e32 v43, v35
	ds_write_b16 v217, v0 offset:192
	v_mul_f32_e32 v0, v18, v42
	v_cvt_pk_bf16_f32 v0, v0, s0
	ds_write_b16 v217, v0 offset:256
	v_mul_f32_e32 v0, v2, v42
	v_cvt_pk_bf16_f32 v0, v0, s0
	s_waitcnt lgkmcnt(4)
	v_rcp_f32_e32 v44, v36
	ds_write_b16 v217, v0 offset:320
	v_mul_f32_e32 v0, v19, v43
	v_cvt_pk_bf16_f32 v0, v0, s0
	ds_write_b16 v217, v0 offset:384
	v_mul_f32_e32 v0, v3, v43
	v_cvt_pk_bf16_f32 v0, v0, s0
	v_rcp_f32_e32 v45, v37
	ds_write_b16 v217, v0 offset:448
	v_mul_f32_e32 v0, v20, v44
	v_cvt_pk_bf16_f32 v0, v0, s0
	ds_write_b16 v217, v0 offset:1024
	v_mul_f32_e32 v0, v4, v44
	v_cvt_pk_bf16_f32 v0, v0, s0
	v_rcp_f32_e32 v46, v38
	ds_write_b16 v217, v0 offset:1088
	v_mul_f32_e32 v0, v21, v45
	v_cvt_pk_bf16_f32 v0, v0, s0
	ds_write_b16 v217, v0 offset:1152
	v_mul_f32_e32 v0, v5, v45
	ds_read_b128 v[32:35], v215 offset:192
	v_cvt_pk_bf16_f32 v0, v0, s0
	v_rcp_f32_e32 v47, v39
	ds_write_b16 v217, v0 offset:1216
	v_mul_f32_e32 v0, v22, v46
	v_cvt_pk_bf16_f32 v0, v0, s0
	ds_write_b16 v217, v0 offset:1280
	v_mul_f32_e32 v0, v6, v46
	v_cvt_pk_bf16_f32 v0, v0, s0
	ds_read_b128 v[36:39], v215 offset:224
	s_waitcnt lgkmcnt(3)
	v_rcp_f32_e32 v32, v32
	ds_write_b16 v217, v0 offset:1344
	v_mul_f32_e32 v0, v23, v47
	v_cvt_pk_bf16_f32 v0, v0, s0
	ds_write_b16 v217, v0 offset:1408
	v_mul_f32_e32 v0, v7, v47
	v_cvt_pk_bf16_f32 v0, v0, s0
	v_rcp_f32_e32 v33, v33
	ds_write_b16 v217, v0 offset:1472
	v_mul_f32_e32 v0, v24, v32
	v_cvt_pk_bf16_f32 v0, v0, s0
	ds_write_b16 v217, v0 offset:2048
	v_mul_f32_e32 v0, v8, v32
	v_cvt_pk_bf16_f32 v0, v0, s0
	v_rcp_f32_e32 v34, v34
	ds_write_b16 v217, v0 offset:2112
	v_mul_f32_e32 v0, v25, v33
	v_cvt_pk_bf16_f32 v0, v0, s0
	ds_write_b16 v217, v0 offset:2176
	v_mul_f32_e32 v0, v9, v33
	v_cvt_pk_bf16_f32 v0, v0, s0
	v_rcp_f32_e32 v35, v35
	ds_write_b16 v217, v0 offset:2240
	v_mul_f32_e32 v0, v26, v34
	v_cvt_pk_bf16_f32 v0, v0, s0
	ds_write_b16 v217, v0 offset:2304
	v_mul_f32_e32 v0, v10, v34
	v_cvt_pk_bf16_f32 v0, v0, s0
	s_waitcnt lgkmcnt(8)
	v_rcp_f32_e32 v36, v36
	ds_write_b16 v217, v0 offset:2368
	v_mul_f32_e32 v0, v27, v35
	v_cvt_pk_bf16_f32 v0, v0, s0
	ds_write_b16 v217, v0 offset:2432
	v_mul_f32_e32 v0, v11, v35
	v_cvt_pk_bf16_f32 v0, v0, s0
	v_rcp_f32_e32 v37, v37
	ds_write_b16 v217, v0 offset:2496
	v_mul_f32_e32 v0, v28, v36
	v_cvt_pk_bf16_f32 v0, v0, s0
	ds_write_b16 v217, v0 offset:3072
	v_mul_f32_e32 v0, v12, v36
	v_cvt_pk_bf16_f32 v0, v0, s0
	v_rcp_f32_e32 v38, v38
	ds_write_b16 v217, v0 offset:3136
	v_mul_f32_e32 v0, v29, v37
	v_cvt_pk_bf16_f32 v0, v0, s0
	ds_write_b16 v217, v0 offset:3200
	v_mul_f32_e32 v0, v13, v37
	v_cvt_pk_bf16_f32 v0, v0, s0
	v_rcp_f32_e32 v39, v39
	ds_write_b16 v217, v0 offset:3264
	v_mul_f32_e32 v0, v30, v38
	v_cvt_pk_bf16_f32 v0, v0, s0
	ds_write_b16 v217, v0 offset:3328
	v_mul_f32_e32 v0, v14, v38
	v_cvt_pk_bf16_f32 v0, v0, s0
	ds_write_b16 v217, v0 offset:3392
	v_mul_f32_e32 v0, v31, v39
	v_cvt_pk_bf16_f32 v0, v0, s0
	v_mul_f32_e32 v16, v16, v40
	ds_write_b16 v217, v0 offset:3456
	v_mul_f32_e32 v0, v15, v39
	v_cvt_pk_bf16_f32 v16, v16, s0
	v_cvt_pk_bf16_f32 v0, v0, s0
	ds_write_b16 v217, v16
	ds_write_b16 v217, v0 offset:3520
	v_mov_b32_e32 v16, v80
	v_mov_b32_e32 v17, v81
	v_lshlrev_b64 v[140:141], 1, v[154:155]
	s_waitcnt lgkmcnt(0)
	v_lshl_add_u64 v[0:1], v[16:17], 0, v[140:141]
	global_load_dwordx4 v[0:3], v[0:1], off
	v_lshlrev_b64 v[142:143], 1, v[156:157]
	v_lshl_add_u64 v[4:5], v[16:17], 0, v[142:143]
	global_load_dwordx4 v[4:7], v[4:5], off
	v_lshlrev_b64 v[166:167], 1, v[158:159]
	v_lshl_add_u64 v[8:9], v[16:17], 0, v[166:167]
	global_load_dwordx4 v[8:11], v[8:9], off
	v_lshlrev_b64 v[168:169], 1, v[160:161]
	v_lshl_add_u64 v[16:17], v[16:17], 0, v[168:169]
	global_load_dwordx4 v[16:19], v[16:17], off
	ds_read_b128 v[12:15], v177
	v_mov_b32_e32 v20, v82
	v_mov_b32_e32 v21, v83
	s_waitcnt lgkmcnt(0)
	v_lshlrev_b32_e32 v22, 16, v12
	v_and_b32_e32 v23, 0xffff0000, v12
	v_lshlrev_b32_e32 v12, 16, v13
	v_and_b32_e32 v13, 0xffff0000, v13
	s_waitcnt vmcnt(3)
	v_lshlrev_b32_e32 v24, 16, v0
	v_and_b32_e32 v25, 0xffff0000, v0
	v_pk_mul_f32 v[22:23], v[22:23], v[24:25]
	v_lshlrev_b32_e32 v24, 16, v3
	v_cvt_pk_bf16_f32 v0, v22, v23
	v_lshlrev_b32_e32 v22, 16, v1
	v_and_b32_e32 v23, 0xffff0000, v1
	v_pk_mul_f32 v[12:13], v[12:13], v[22:23]
	v_lshlrev_b32_e32 v22, 16, v2
	v_cvt_pk_bf16_f32 v1, v12, v13
	v_lshlrev_b32_e32 v12, 16, v14
	v_and_b32_e32 v13, 0xffff0000, v14
	v_and_b32_e32 v23, 0xffff0000, v2
	v_pk_mul_f32 v[12:13], v[12:13], v[22:23]
	v_lshlrev_b32_e32 v22, 16, v15
	v_cvt_pk_bf16_f32 v2, v12, v13
	v_and_b32_e32 v23, 0xffff0000, v15
	ds_read_b128 v[12:15], v176
	v_and_b32_e32 v25, 0xffff0000, v3
	v_pk_mul_f32 v[22:23], v[22:23], v[24:25]
	s_nop 0
	v_cvt_pk_bf16_f32 v3, v22, v23
	v_lshl_add_u64 v[22:23], v[20:21], 0, v[140:141]
	global_store_dwordx4 v[22:23], v[0:3], off sc1
	s_waitcnt lgkmcnt(0)
	s_nop 0
	v_lshlrev_b32_e32 v0, 16, v12
	v_and_b32_e32 v1, 0xffff0000, v12
	s_waitcnt vmcnt(3)
	v_lshlrev_b32_e32 v2, 16, v4
	v_and_b32_e32 v3, 0xffff0000, v4
	v_pk_mul_f32 v[0:1], v[0:1], v[2:3]
	v_lshlrev_b32_e32 v2, 16, v13
	v_and_b32_e32 v3, 0xffff0000, v13
	v_lshlrev_b32_e32 v4, 16, v5
	v_and_b32_e32 v5, 0xffff0000, v5
	v_pk_mul_f32 v[2:3], v[2:3], v[4:5]
	v_cvt_pk_bf16_f32 v0, v0, v1
	v_cvt_pk_bf16_f32 v1, v2, v3
	v_lshlrev_b32_e32 v2, 16, v14
	v_and_b32_e32 v3, 0xffff0000, v14
	v_lshlrev_b32_e32 v4, 16, v6
	v_and_b32_e32 v5, 0xffff0000, v6
	v_pk_mul_f32 v[2:3], v[2:3], v[4:5]
	v_lshlrev_b32_e32 v12, 16, v15
	v_and_b32_e32 v13, 0xffff0000, v15
	v_lshlrev_b32_e32 v14, 16, v7
	v_and_b32_e32 v15, 0xffff0000, v7
	ds_read_b128 v[4:7], v175
	v_pk_mul_f32 v[12:13], v[12:13], v[14:15]
	v_cvt_pk_bf16_f32 v2, v2, v3
	v_cvt_pk_bf16_f32 v3, v12, v13
	v_lshl_add_u64 v[12:13], v[20:21], 0, v[142:143]
	global_store_dwordx4 v[12:13], v[0:3], off sc1
	s_waitcnt lgkmcnt(0)
	s_nop 0
	v_lshlrev_b32_e32 v0, 16, v4
	v_and_b32_e32 v1, 0xffff0000, v4
	s_waitcnt vmcnt(3)
	v_lshlrev_b32_e32 v2, 16, v8
	v_and_b32_e32 v3, 0xffff0000, v8
	v_pk_mul_f32 v[0:1], v[0:1], v[2:3]
	v_lshlrev_b32_e32 v2, 16, v5
	v_and_b32_e32 v3, 0xffff0000, v5
	v_lshlrev_b32_e32 v4, 16, v9
	v_and_b32_e32 v5, 0xffff0000, v9
	v_pk_mul_f32 v[2:3], v[2:3], v[4:5]
	v_cvt_pk_bf16_f32 v0, v0, v1
	v_cvt_pk_bf16_f32 v1, v2, v3
	v_lshlrev_b32_e32 v2, 16, v6
	v_and_b32_e32 v3, 0xffff0000, v6
	v_lshlrev_b32_e32 v4, 16, v10
	v_and_b32_e32 v5, 0xffff0000, v10
	v_pk_mul_f32 v[2:3], v[2:3], v[4:5]
	v_lshlrev_b32_e32 v8, 16, v7
	v_and_b32_e32 v9, 0xffff0000, v7
	ds_read_b128 v[4:7], v174
	v_lshlrev_b32_e32 v10, 16, v11
	v_and_b32_e32 v11, 0xffff0000, v11
	v_pk_mul_f32 v[8:9], v[8:9], v[10:11]
	v_cvt_pk_bf16_f32 v2, v2, v3
	v_cvt_pk_bf16_f32 v3, v8, v9
	v_lshl_add_u64 v[8:9], v[20:21], 0, v[166:167]
	global_store_dwordx4 v[8:9], v[0:3], off sc1
	s_waitcnt lgkmcnt(0)
	s_nop 0
	v_lshlrev_b32_e32 v0, 16, v4
	v_and_b32_e32 v1, 0xffff0000, v4
	s_waitcnt vmcnt(3)
	v_lshlrev_b32_e32 v2, 16, v16
	v_and_b32_e32 v3, 0xffff0000, v16
	v_pk_mul_f32 v[0:1], v[0:1], v[2:3]
	v_lshlrev_b32_e32 v2, 16, v5
	v_and_b32_e32 v3, 0xffff0000, v5
	v_lshlrev_b32_e32 v4, 16, v17
	v_and_b32_e32 v5, 0xffff0000, v17
	v_pk_mul_f32 v[2:3], v[2:3], v[4:5]
	v_cvt_pk_bf16_f32 v0, v0, v1
	v_cvt_pk_bf16_f32 v1, v2, v3
	v_lshlrev_b32_e32 v2, 16, v6
	v_and_b32_e32 v3, 0xffff0000, v6
	v_lshlrev_b32_e32 v4, 16, v18
	v_and_b32_e32 v5, 0xffff0000, v18
	v_pk_mul_f32 v[2:3], v[2:3], v[4:5]
	v_lshlrev_b32_e32 v4, 16, v7
	v_and_b32_e32 v5, 0xffff0000, v7
	v_lshlrev_b32_e32 v6, 16, v19
	v_and_b32_e32 v7, 0xffff0000, v19
	v_pk_mul_f32 v[4:5], v[4:5], v[6:7]
	v_cvt_pk_bf16_f32 v2, v2, v3
	v_cvt_pk_bf16_f32 v3, v4, v5
	v_lshl_add_u64 v[4:5], v[20:21], 0, v[168:169]
	global_store_dwordx4 v[4:5], v[0:3], off sc1
	s_waitcnt lgkmcnt(0)
	s_barrier
	s_cmp_eq_u32 s78, 3
	s_cbranch_scc1 .LBB0_668
	v_mov_b32_e32 v0, v48
	v_mov_b32_e32 v1, v49
	v_mov_b32_e32 v2, v50
	v_mov_b32_e32 v3, v51
	v_mov_b32_e32 v4, v52
	v_mov_b32_e32 v5, v53
	v_mov_b32_e32 v6, v54
	v_mov_b32_e32 v7, v55
	v_mov_b32_e32 v8, v56
	v_mov_b32_e32 v9, v57
	v_mov_b32_e32 v10, v58
	v_mov_b32_e32 v11, v59
	v_mov_b32_e32 v12, v60
	v_mov_b32_e32 v13, v61
	v_mov_b32_e32 v14, v62
	v_mov_b32_e32 v15, v63
	v_mov_b32_e32 v16, v64
	v_mov_b32_e32 v17, v65
	v_mov_b32_e32 v18, v66
	v_mov_b32_e32 v19, v67
	v_mov_b32_e32 v20, v68
	v_mov_b32_e32 v21, v69
	v_mov_b32_e32 v22, v70
	v_mov_b32_e32 v23, v71
	s_branch .Lnbp_join

.Lnbp_join:
	v_readlane_b32 s44, v246, 58
	v_readlane_b32 s45, v246, 59
	s_andn2_b64 vcc, exec, s[44:45]
	s_waitcnt vmcnt(9)
	v_mov_b32_e32 v24, v0
	v_mov_b32_e32 v25, v2
	v_mov_b32_e32 v2, v1
	s_waitcnt vmcnt(8)
	v_mov_b32_e32 v0, v4
	v_mov_b32_e32 v1, v6
	v_mov_b32_e32 v6, v5
	s_waitcnt vmcnt(6)
	v_mov_b32_e32 v4, v12
	v_mov_b32_e32 v5, v14
	v_mov_b32_e32 v14, v13
	v_mov_b32_e32 v12, v8
	v_mov_b32_e32 v13, v10
	v_mov_b32_e32 v10, v9
	s_waitcnt vmcnt(5)
	v_and_b32_e32 v9, 0xffff0000, v16
	v_lshlrev_b32_e32 v8, 16, v16
	s_waitcnt vmcnt(4)
	v_and_b32_e32 v27, 0xffff0000, v20
	v_lshlrev_b32_e32 v26, 16, v20
	v_and_b32_e32 v29, 0xffff0000, v17
	v_lshlrev_b32_e32 v28, 16, v17
	v_and_b32_e32 v17, 0xffff0000, v21
	v_lshlrev_b32_e32 v16, 16, v21
	v_and_b32_e32 v21, 0xffff0000, v18
	v_lshlrev_b32_e32 v20, 16, v18
	v_and_b32_e32 v31, 0xffff0000, v22
	v_lshlrev_b32_e32 v30, 16, v22
	v_and_b32_e32 v33, 0xffff0000, v19
	v_lshlrev_b32_e32 v32, 16, v19
	v_and_b32_e32 v19, 0xffff0000, v23
	v_lshlrev_b32_e32 v18, 16, v23
	v_pk_mul_f32 v[22:23], v[2:3], v[26:27]
	v_pk_mul_f32 v[26:27], v[24:25], v[26:27]
	v_pk_mul_f32 v[34:35], v[6:7], v[16:17]
	v_pk_mul_f32 v[16:17], v[0:1], v[16:17]
	v_pk_mul_f32 v[36:37], v[14:15], v[30:31]
	v_pk_mul_f32 v[30:31], v[4:5], v[30:31]
	v_pk_mul_f32 v[38:39], v[10:11], v[18:19]
	v_pk_mul_f32 v[18:19], v[12:13], v[18:19]
	v_pk_fma_f32 v[22:23], v[24:25], v[8:9], v[22:23] neg_lo:[0,0,1] neg_hi:[0,0,1]
	v_pk_fma_f32 v[2:3], v[2:3], v[8:9], v[26:27]
	v_pk_fma_f32 v[0:1], v[0:1], v[28:29], v[34:35] neg_lo:[0,0,1] neg_hi:[0,0,1]
	v_pk_fma_f32 v[6:7], v[6:7], v[28:29], v[16:17]
	v_pk_fma_f32 v[4:5], v[4:5], v[20:21], v[36:37] neg_lo:[0,0,1] neg_hi:[0,0,1]
	v_pk_fma_f32 v[8:9], v[14:15], v[20:21], v[30:31]
	v_pk_fma_f32 v[12:13], v[12:13], v[32:33], v[38:39] neg_lo:[0,0,1] neg_hi:[0,0,1]
	v_pk_fma_f32 v[10:11], v[10:11], v[32:33], v[18:19]
	v_cvt_pk_bf16_f32 v108, v22, v23
	v_cvt_pk_bf16_f32 v109, v0, v1
	v_cvt_pk_bf16_f32 v110, v4, v5
	v_cvt_pk_bf16_f32 v111, v12, v13
	v_cvt_pk_bf16_f32 v100, v2, v3
	v_cvt_pk_bf16_f32 v101, v6, v7
	v_cvt_pk_bf16_f32 v102, v8, v9
	v_cvt_pk_bf16_f32 v103, v10, v11
	s_cbranch_vccnz .LBB0_558
	s_waitcnt vmcnt(3)
	v_lshlrev_b32_e32 v0, 16, v116
	v_fma_f32 v0, v0, v0, 0
	v_and_b32_e32 v1, 0xffff0000, v116
	v_fmac_f32_e32 v0, v1, v1
	v_lshlrev_b32_e32 v1, 16, v117
	v_fmac_f32_e32 v0, v1, v1
	v_and_b32_e32 v1, 0xffff0000, v117
	v_fmac_f32_e32 v0, v1, v1
	v_lshlrev_b32_e32 v1, 16, v118
	v_fmac_f32_e32 v0, v1, v1
	v_and_b32_e32 v1, 0xffff0000, v118
	v_fmac_f32_e32 v0, v1, v1
	v_lshlrev_b32_e32 v1, 16, v119
	v_fmac_f32_e32 v0, v1, v1
	v_and_b32_e32 v1, 0xffff0000, v119
	v_fmac_f32_e32 v0, v1, v1
	s_waitcnt vmcnt(2)
	v_lshlrev_b32_e32 v1, 16, v112
	v_fmac_f32_e32 v0, v1, v1
	v_and_b32_e32 v1, 0xffff0000, v112
	v_fmac_f32_e32 v0, v1, v1
	v_lshlrev_b32_e32 v1, 16, v113
	v_fmac_f32_e32 v0, v1, v1
	v_and_b32_e32 v1, 0xffff0000, v113
	v_fmac_f32_e32 v0, v1, v1
	v_lshlrev_b32_e32 v1, 16, v114
	v_fmac_f32_e32 v0, v1, v1
	v_and_b32_e32 v1, 0xffff0000, v114
	v_fmac_f32_e32 v0, v1, v1
	v_lshlrev_b32_e32 v1, 16, v115
	v_fmac_f32_e32 v0, v1, v1
	v_and_b32_e32 v1, 0xffff0000, v115
	v_fmac_f32_e32 v0, v1, v1
	s_waitcnt vmcnt(1)
	v_lshlrev_b32_e32 v1, 16, v104
	v_fmac_f32_e32 v0, v1, v1
	v_and_b32_e32 v1, 0xffff0000, v104
	v_fmac_f32_e32 v0, v1, v1
	v_lshlrev_b32_e32 v1, 16, v105
	v_fmac_f32_e32 v0, v1, v1
	v_and_b32_e32 v1, 0xffff0000, v105
	v_fmac_f32_e32 v0, v1, v1
	v_lshlrev_b32_e32 v1, 16, v106
	v_fmac_f32_e32 v0, v1, v1
	v_and_b32_e32 v1, 0xffff0000, v106
	v_fmac_f32_e32 v0, v1, v1
	v_lshlrev_b32_e32 v1, 16, v107
	v_fmac_f32_e32 v0, v1, v1
	v_and_b32_e32 v1, 0xffff0000, v107
	v_fmac_f32_e32 v0, v1, v1
	s_waitcnt vmcnt(0)
	v_lshlrev_b32_e32 v1, 16, v96
	v_fmac_f32_e32 v0, v1, v1
	v_and_b32_e32 v1, 0xffff0000, v96
	v_fmac_f32_e32 v0, v1, v1
	v_lshlrev_b32_e32 v1, 16, v97
	v_fmac_f32_e32 v0, v1, v1
	v_and_b32_e32 v1, 0xffff0000, v97
	v_fmac_f32_e32 v0, v1, v1
	v_lshlrev_b32_e32 v1, 16, v98
	v_fmac_f32_e32 v0, v1, v1
	v_and_b32_e32 v1, 0xffff0000, v98
	v_fmac_f32_e32 v0, v1, v1
	v_lshlrev_b32_e32 v1, 16, v99
	v_fmac_f32_e32 v0, v1, v1
	v_and_b32_e32 v1, 0xffff0000, v99
	v_fmac_f32_e32 v0, v1, v1
	v_lshlrev_b32_e32 v1, 16, v108
	v_fmac_f32_e32 v0, v1, v1
	v_and_b32_e32 v1, 0xffff0000, v108
	v_fmac_f32_e32 v0, v1, v1
	v_lshlrev_b32_e32 v1, 16, v109
	v_fmac_f32_e32 v0, v1, v1
	v_and_b32_e32 v1, 0xffff0000, v109
	v_fmac_f32_e32 v0, v1, v1
	v_lshlrev_b32_e32 v1, 16, v110
	v_fmac_f32_e32 v0, v1, v1
	v_and_b32_e32 v1, 0xffff0000, v110
	v_fmac_f32_e32 v0, v1, v1
	v_lshlrev_b32_e32 v1, 16, v111
	v_fmac_f32_e32 v0, v1, v1
	v_and_b32_e32 v1, 0xffff0000, v111
	v_fmac_f32_e32 v0, v1, v1
	v_lshlrev_b32_e32 v1, 16, v100
	v_fmac_f32_e32 v0, v1, v1
	v_and_b32_e32 v1, 0xffff0000, v100
	v_fmac_f32_e32 v0, v1, v1
	v_lshlrev_b32_e32 v1, 16, v101
	v_fmac_f32_e32 v0, v1, v1
	v_and_b32_e32 v1, 0xffff0000, v101
	v_fmac_f32_e32 v0, v1, v1
	v_lshlrev_b32_e32 v1, 16, v102
	v_fmac_f32_e32 v0, v1, v1
	v_and_b32_e32 v1, 0xffff0000, v102
	v_fmac_f32_e32 v0, v1, v1
	v_lshlrev_b32_e32 v1, 16, v103
	v_fmac_f32_e32 v0, v1, v1
	v_and_b32_e32 v1, 0xffff0000, v103
	s_ashr_i32 s1, s0, 31
	v_fmac_f32_e32 v0, v1, v1
	s_lshl_b64 s[0:1], s[0:1], 9
	s_lshl_b32 s44, s56, 7
	v_mov_b32_e32 v1, v0
	s_ashr_i32 s45, s44, 31
	s_nop 0
	v_permlane32_swap_b32_e32 v0, v1
	v_add_f32_e32 v0, v0, v1
	s_mov_b32 s0, 0x45610000
	v_max_f32_e32 v0, v0, v0
	v_max_f32_e32 v1, v247, v247
	v_max_f32_e32 v4, v248, v248
	v_max_f32_e32 v3, v249, v249
	v_max_f32_e32 v2, v254, v254
	s_nop 0
	v_max_f32_e32 v2, v3, v2
	s_nop 1
	v_max_f32_dpp v0, v0, v0 quad_perm:[1,0,3,2] row_mask:0xf bank_mask:0xf
	v_max_f32_dpp v1, v1, v1 quad_perm:[1,0,3,2] row_mask:0xf bank_mask:0xf
	v_max_f32_dpp v4, v4, v4 quad_perm:[1,0,3,2] row_mask:0xf bank_mask:0xf
	v_max_f32_dpp v2, v2, v2 quad_perm:[1,0,3,2] row_mask:0xf bank_mask:0xf
	v_max_f32_dpp v0, v0, v0 quad_perm:[2,3,0,1] row_mask:0xf bank_mask:0xf
	v_max_f32_dpp v1, v1, v1 quad_perm:[2,3,0,1] row_mask:0xf bank_mask:0xf
	v_max_f32_dpp v4, v4, v4 quad_perm:[2,3,0,1] row_mask:0xf bank_mask:0xf
	v_max_f32_dpp v2, v2, v2 quad_perm:[2,3,0,1] row_mask:0xf bank_mask:0xf
	v_max_f32_dpp v0, v0, v0 row_half_mirror row_mask:0xf bank_mask:0xf
	v_max_f32_dpp v1, v1, v1 row_half_mirror row_mask:0xf bank_mask:0xf
	v_max_f32_dpp v4, v4, v4 row_half_mirror row_mask:0xf bank_mask:0xf
	v_max_f32_dpp v2, v2, v2 row_half_mirror row_mask:0xf bank_mask:0xf
	v_max_f32_dpp v0, v0, v0 row_mirror row_mask:0xf bank_mask:0xf
	v_max_f32_dpp v1, v1, v1 row_mirror row_mask:0xf bank_mask:0xf
	v_max_f32_dpp v4, v4, v4 row_mirror row_mask:0xf bank_mask:0xf
	v_max_f32_dpp v2, v2, v2 row_mirror row_mask:0xf bank_mask:0xf
	v_max_f32_dpp v0, v0, v0 row_bcast:15 row_mask:0xa bank_mask:0xf
	v_max_f32_dpp v1, v1, v1 row_bcast:15 row_mask:0xa bank_mask:0xf
	v_max_f32_dpp v4, v4, v4 row_bcast:15 row_mask:0xa bank_mask:0xf
	v_max_f32_dpp v2, v2, v2 row_bcast:15 row_mask:0xa bank_mask:0xf
	v_max_f32_dpp v0, v0, v0 row_bcast:31 row_mask:0xc bank_mask:0xf
	v_max_f32_dpp v1, v1, v1 row_bcast:31 row_mask:0xc bank_mask:0xf
	v_max_f32_dpp v4, v4, v4 row_bcast:31 row_mask:0xc bank_mask:0xf
	v_max_f32_dpp v2, v2, v2 row_bcast:31 row_mask:0xc bank_mask:0xf
	v_add_f32_e32 v1, v1, v4
	v_add_f32_e32 v1, v2, v1
	v_mul_f32_e32 v0, v0, v1
	v_mul_f32_e32 v0, 0x3f866666, v0
	v_cmp_ge_f32_e32 vcc, s0, v0
	s_nop 1
	v_cndmask_b32_e64 v0, 0, 1, vcc
	s_nop 0
	v_readlane_b32 s0, v0, 63
	s_bitcmp1_b32 s0, 0
	s_cselect_b64 s[44:45], -1, 0
	s_branch .LBB0_559
